# retention O-store section: batched LDS reads + 32-bit store offsets; storing waves keep their 32 stores in flight across the chunk-top waits
# speedup vs baseline: 1.0063x; 1.0063x over previous
; template <bool DRY>
; DI void ret_phase(LAS unsigned char* lds, const bf16* Q, const bf16* Kb, bf16* V, const float* qg, const float* kg, int G, int blk) {
;     ...
;     for (int it = blk; it < 512; it += G) {
;         const int loc = it & 255, rnd = it >> 8;
;         const int vs = (loc >> 3) & 3, bh = rnd * 64 + (loc & 7) * 8 + (loc >> 5);
;         const int b = bh >> 3, h = bh & 7;
;         const float gam = 1.f - exp2f(-5.f - (float)h), l2g = log2f(gam), gC = exp2f(64.f * l2g);
;         f32x16 st[4];
; #pragma unroll
;         for (int d = 0; d < 4; ++d)
; #pragma unroll
;             for (int i = 0; i < 16; ++i) st[d][i] = 0.f;
;         RET_LOAD(0);
;         for (int n = 0; n < 32; ++n) {
;             const int t0 = n * 64;
;             RET_STAGE();
;             __syncthreads();
;             if (n < 31) RET_LOAD(n + 1);
.LBB0_578:
	v_add_u32_e32 v64, v150, v140
	v_add_u32_e32 v65, v152, v140
	s_cmp_eq_u64 s[42:43], 0
	s_cbranch_scc1 .Lret_top_norm
	s_cmp_eq_u32 s76, 0
	s_cbranch_scc1 .Lret_top_norm
	s_waitcnt vmcnt(41)
	ds_write_b128 v64, v[96:99]
	s_waitcnt vmcnt(40)
	ds_write_b128 v64, v[100:103] offset:256
	s_waitcnt vmcnt(39)
	ds_write_b128 v65, v[104:107] offset:33792
	s_waitcnt vmcnt(38)
	ds_write_b128 v65, v[108:111] offset:34048
	s_waitcnt vmcnt(37)
	ds_write_b128 v64, v[112:115] offset:16896
	s_waitcnt vmcnt(35)
	ds_write_b128 v64, v[116:119] offset:17152
	ds_write_b128 v173, v[120:123] offset:33792
	s_waitcnt vmcnt(34)
	ds_write_b128 v173, v[124:127] offset:34048
	s_waitcnt vmcnt(33)
	ds_write_b128 v174, v[128:131]
	s_waitcnt vmcnt(32)
	ds_write_b128 v174, v[132:135] offset:128
	s_branch .Lret_top_join
.Lret_top_norm:
	s_waitcnt vmcnt(9)
	ds_write_b128 v64, v[96:99]
	s_waitcnt vmcnt(8)
	ds_write_b128 v64, v[100:103] offset:256
	s_waitcnt vmcnt(7)
	ds_write_b128 v65, v[104:107] offset:33792
	s_waitcnt vmcnt(6)
	ds_write_b128 v65, v[108:111] offset:34048
	s_waitcnt vmcnt(5)
	ds_write_b128 v64, v[112:115] offset:16896
	s_waitcnt vmcnt(3)
	ds_write_b128 v64, v[116:119] offset:17152
	ds_write_b128 v173, v[120:123] offset:33792
	s_waitcnt vmcnt(2)
	ds_write_b128 v173, v[124:127] offset:34048
	s_waitcnt vmcnt(1)
	ds_write_b128 v174, v[128:131]
	s_waitcnt vmcnt(0)
	ds_write_b128 v174, v[132:135] offset:128
.Lret_top_join:
	s_cmpk_eq_i32 s76, 0x7c0
	s_waitcnt lgkmcnt(0)
	s_barrier
	s_cbranch_scc1 .LBB0_580
	v_readlane_b32 s80, v254, 24
	v_readlane_b32 s86, v254, 30
	v_readlane_b32 s87, v254, 31
	v_readlane_b32 s81, v254, 25
	v_readlane_b32 s82, v254, 26
	v_lshl_add_u64 v[64:65], s[86:87], 0, v[164:165]
	v_add_co_u32_e32 v66, vcc, 0xe940000, v64
	v_readlane_b32 s83, v254, 27
	s_nop 0
	v_addc_co_u32_e32 v67, vcc, 0, v65, vcc
	global_load_dwordx4 v[96:99], v[66:67], off
	global_load_dwordx4 v[100:103], v[66:67], off offset:256
	v_add_co_u32_e32 v66, vcc, 0x16940000, v64
	v_readlane_b32 s84, v254, 28
	s_nop 0
	v_addc_co_u32_e32 v67, vcc, 0, v65, vcc
	global_load_dwordx4 v[104:107], v[66:67], off
	global_load_dwordx4 v[108:111], v[66:67], off offset:256
	v_add_co_u32_e32 v66, vcc, 0xe960000, v64
	v_readlane_b32 s85, v254, 29
	s_nop 0
	v_addc_co_u32_e32 v67, vcc, 0, v65, vcc
	v_add_co_u32_e32 v64, vcc, 0x16960000, v64
	global_load_dwordx4 v[112:115], v[66:67], off
	global_load_dwordx4 v[116:119], v[66:67], off offset:256
	v_addc_co_u32_e32 v65, vcc, 0, v65, vcc
	global_load_dwordx4 v[120:123], v[64:65], off
	global_load_dwordx4 v[124:127], v[64:65], off offset:256
	v_lshl_add_u64 v[64:65], s[86:87], 0, v[162:163]
	v_add_co_u32_e32 v64, vcc, 0x1e980000, v64
	s_nop 1
	v_addc_co_u32_e32 v65, vcc, 0, v65, vcc
	global_load_dwordx4 v[128:131], v[64:65], off
	global_load_dwordx4 v[132:135], v[64:65], off offset:128

; DI bf16 f2bf(float f) { return (bf16)(pk2(f, 0.f) & 0xffffu); }
; DI int crow(int i, int hh) { return (i & 3) + 8 * (i >> 2) + 4 * hh; }
; template <bool DRY>
; DI void ret_phase(LAS unsigned char* lds, const bf16* Q, const bf16* Kb, bf16* V, const float* qg, const float* kg, int G, int blk) {
;     ...
;             __syncthreads();
;             if (dh == 0 && (!DRY || gC > 2.f)) {
; #pragma unroll
;                 for (int qt = 0; qt < 2; ++qt)
; #pragma unroll
;                     for (int i = 0; i < 16; ++i) {
;                         const int q = 32 * qt + crow(i, hh);
;                         const float v = Op[qt][i] + Red[c * 2048 + q * 32 + r];
;                         V[((size_t)b * SEQ + t0 + q) * 4096 + h * 512 + vs * 128 + 32 * c + r] = f2bf(v);
;                     }
;             }
.LBB0_590:
	s_andn2_b64 vcc, exec, s[42:43]
	s_waitcnt lgkmcnt(0)
	s_barrier
	s_cbranch_vccnz .LBB0_577
	v_add_u32_e32 v159, v168, v141
	ds_read_b32 v220, v159
	ds_read_b32 v221, v181
	ds_read_b32 v222, v182
	ds_read_b32 v223, v183
	ds_read_b32 v224, v184
	ds_read_b32 v225, v185
	ds_read_b32 v226, v186
	ds_read_b32 v227, v187
	ds_read_b32 v228, v188
	ds_read_b32 v229, v189
	ds_read_b32 v230, v190
	ds_read_b32 v231, v191
	ds_read_b32 v232, v192
	ds_read_b32 v233, v193
	ds_read_b32 v234, v194
	ds_read_b32 v235, v195
	ds_read_b32 v236, v198
	ds_read_b32 v237, v199
	ds_read_b32 v238, v200
	ds_read_b32 v239, v201
	ds_read_b32 v240, v202
	ds_read_b32 v241, v203
	ds_read_b32 v242, v204
	ds_read_b32 v243, v205
	ds_read_b32 v244, v206
	ds_read_b32 v245, v207
	ds_read_b32 v246, v208
	ds_read_b32 v247, v209
	ds_read_b32 v248, v210
	ds_read_b32 v249, v211
	ds_read_b32 v250, v212
	ds_read_b32 v251, v213
	v_add_u32_e32 v166, s76, v148
	v_or_b32_e32 v166, s74, v166
	v_lshlrev_b32_e32 v166, 13, v166
	v_or_b32_e32 v166, v166, v218
	s_waitcnt lgkmcnt(15)
	v_add_f32_e32 v220, v80, v220
	v_cvt_pk_bf16_f32 v220, v220, s0
	global_store_short v166, v220, s[60:61]
	v_add_f32_e32 v221, v81, v221
	v_cvt_pk_bf16_f32 v221, v221, s0
	v_add_u32_e32 v81, 0x2000, v166
	global_store_short v81, v221, s[60:61]
	v_add_f32_e32 v222, v82, v222
	v_cvt_pk_bf16_f32 v222, v222, s0
	v_add_u32_e32 v82, 0x4000, v166
	global_store_short v82, v222, s[60:61]
	v_add_f32_e32 v223, v83, v223
	v_cvt_pk_bf16_f32 v223, v223, s0
	v_add_u32_e32 v83, 0x6000, v166
	global_store_short v83, v223, s[60:61]
	v_add_f32_e32 v224, v84, v224
	v_cvt_pk_bf16_f32 v224, v224, s0
	v_add_u32_e32 v84, 0x10000, v166
	global_store_short v84, v224, s[60:61]
	v_add_f32_e32 v225, v85, v225
	v_cvt_pk_bf16_f32 v225, v225, s0
	v_add_u32_e32 v85, 0x12000, v166
	global_store_short v85, v225, s[60:61]
	v_add_f32_e32 v226, v86, v226
	v_cvt_pk_bf16_f32 v226, v226, s0
	v_add_u32_e32 v86, 0x14000, v166
	global_store_short v86, v226, s[60:61]
	v_add_f32_e32 v227, v87, v227
	v_cvt_pk_bf16_f32 v227, v227, s0
	v_add_u32_e32 v87, 0x16000, v166
	global_store_short v87, v227, s[60:61]
	v_add_f32_e32 v228, v88, v228
	v_cvt_pk_bf16_f32 v228, v228, s0
	v_add_u32_e32 v88, 0x20000, v166
	global_store_short v88, v228, s[60:61]
	v_add_f32_e32 v229, v89, v229
	v_cvt_pk_bf16_f32 v229, v229, s0
	v_add_u32_e32 v89, 0x22000, v166
	global_store_short v89, v229, s[60:61]
	v_add_f32_e32 v230, v90, v230
	v_cvt_pk_bf16_f32 v230, v230, s0
	v_add_u32_e32 v90, 0x24000, v166
	global_store_short v90, v230, s[60:61]
	v_add_f32_e32 v231, v91, v231
	v_cvt_pk_bf16_f32 v231, v231, s0
	v_add_u32_e32 v91, 0x26000, v166
	global_store_short v91, v231, s[60:61]
	v_add_f32_e32 v232, v92, v232
	v_cvt_pk_bf16_f32 v232, v232, s0
	v_add_u32_e32 v92, 0x30000, v166
	global_store_short v92, v232, s[60:61]
	v_add_f32_e32 v233, v93, v233
	v_cvt_pk_bf16_f32 v233, v233, s0
	v_add_u32_e32 v93, 0x32000, v166
	global_store_short v93, v233, s[60:61]
	v_add_f32_e32 v234, v94, v234
	v_cvt_pk_bf16_f32 v234, v234, s0
	v_add_u32_e32 v94, 0x34000, v166
	global_store_short v94, v234, s[60:61]
	v_add_f32_e32 v235, v95, v235
	v_cvt_pk_bf16_f32 v235, v235, s0
	v_add_u32_e32 v95, 0x36000, v166
	global_store_short v95, v235, s[60:61]
	v_add_f32_e32 v236, v64, v236
	v_cvt_pk_bf16_f32 v236, v236, s0
	v_add_u32_e32 v64, 0x40000, v166
	global_store_short v64, v236, s[60:61]
	s_waitcnt lgkmcnt(0)
	v_add_f32_e32 v237, v65, v237
	v_cvt_pk_bf16_f32 v237, v237, s0
	v_add_u32_e32 v65, 0x42000, v166
	global_store_short v65, v237, s[60:61]
	v_add_f32_e32 v238, v66, v238
	v_cvt_pk_bf16_f32 v238, v238, s0
	v_add_u32_e32 v66, 0x44000, v166
	global_store_short v66, v238, s[60:61]
	v_add_f32_e32 v239, v67, v239
	v_cvt_pk_bf16_f32 v239, v239, s0
	v_add_u32_e32 v67, 0x46000, v166
	global_store_short v67, v239, s[60:61]
	v_add_f32_e32 v240, v68, v240
	v_cvt_pk_bf16_f32 v240, v240, s0
	v_add_u32_e32 v68, 0x50000, v166
	global_store_short v68, v240, s[60:61]
	v_add_f32_e32 v241, v69, v241
	v_cvt_pk_bf16_f32 v241, v241, s0
	v_add_u32_e32 v69, 0x52000, v166
	global_store_short v69, v241, s[60:61]
	v_add_f32_e32 v242, v70, v242
	v_cvt_pk_bf16_f32 v242, v242, s0
	v_add_u32_e32 v70, 0x54000, v166
	global_store_short v70, v242, s[60:61]
	v_add_f32_e32 v243, v71, v243
	v_cvt_pk_bf16_f32 v243, v243, s0
	v_add_u32_e32 v71, 0x56000, v166
	global_store_short v71, v243, s[60:61]
	v_add_f32_e32 v244, v72, v244
	v_cvt_pk_bf16_f32 v244, v244, s0
	v_add_u32_e32 v72, 0x60000, v166
	global_store_short v72, v244, s[60:61]
	v_add_f32_e32 v245, v73, v245
	v_cvt_pk_bf16_f32 v245, v245, s0
	v_add_u32_e32 v73, 0x62000, v166
	global_store_short v73, v245, s[60:61]
	v_add_f32_e32 v246, v74, v246
	v_cvt_pk_bf16_f32 v246, v246, s0
	v_add_u32_e32 v74, 0x64000, v166
	global_store_short v74, v246, s[60:61]
	v_add_f32_e32 v247, v75, v247
	v_cvt_pk_bf16_f32 v247, v247, s0
	v_add_u32_e32 v75, 0x66000, v166
	global_store_short v75, v247, s[60:61]
	v_add_f32_e32 v248, v76, v248
	v_cvt_pk_bf16_f32 v248, v248, s0
	v_add_u32_e32 v76, 0x70000, v166
	global_store_short v76, v248, s[60:61]
	v_add_f32_e32 v249, v77, v249
	v_cvt_pk_bf16_f32 v249, v249, s0
	v_add_u32_e32 v77, 0x72000, v166
	global_store_short v77, v249, s[60:61]
	v_add_f32_e32 v250, v78, v250
	v_cvt_pk_bf16_f32 v250, v250, s0
	v_add_u32_e32 v78, 0x74000, v166
	global_store_short v78, v250, s[60:61]
	v_add_f32_e32 v251, v79, v251
	v_cvt_pk_bf16_f32 v251, v251, s0
	v_add_u32_e32 v79, 0x76000, v166
	global_store_short v79, v251, s[60:61]
	s_branch .LBB0_577
